# LN2 rewritten: gamma/beta hoisted, two row buffers, counted waits (stores never waited for), DPP row_bcast reductions
# speedup vs baseline: 1.0092x; 1.0022x over previous
.Lvsw_skip_gb:
	v_readlane_b32 s100, v252, s39
	v_readlane_b32 s101, v253, s39
	v_ashrrev_i32_e32 v139, 31, v138
	v_lshl_add_u32 v173, s18, 1, v145
	s_lshl_b32 s18, s11, 7
	v_lshlrev_b64 v[138:139], 10, v[138:139]
	v_lshl_add_u64 v[138:139], v[138:139], 0, s[18:19]
	s_lshl_b32 s18, s11, 21
	s_waitcnt lgkmcnt(7)
	v_lshlrev_b32_sdwa v72, v141, v153 dst_sel:DWORD dst_unused:UNUSED_PAD src0_sel:DWORD src1_sel:WORD_0
	s_waitcnt vmcnt(7)
	v_cvt_pk_f32_fp8_e32 v[36:37], v28
	v_cvt_pk_f32_fp8_sdwa v[38:39], v28 src0_sel:WORD_1
	v_cvt_pk_f32_fp8_e32 v[40:41], v29
	v_cvt_pk_f32_fp8_sdwa v[28:29], v29 src0_sel:WORD_1
	v_cvt_pk_f32_fp8_e32 v[42:43], v30
	v_cvt_pk_f32_fp8_sdwa v[44:45], v30 src0_sel:WORD_1
	v_cvt_pk_f32_fp8_e32 v[48:49], v31
	v_cvt_pk_f32_fp8_sdwa v[50:51], v31 src0_sel:WORD_1
	v_lshl_add_u64 v[162:163], v[32:33], 0, s[18:19]
	s_waitcnt vmcnt(6)
	v_cvt_pk_f32_fp8_e32 v[30:31], v20
	v_cvt_pk_f32_fp8_sdwa v[46:47], v20 src0_sel:WORD_1
	v_cvt_pk_f32_fp8_e32 v[52:53], v21
	v_cvt_pk_f32_fp8_sdwa v[54:55], v21 src0_sel:WORD_1
	v_cvt_pk_f32_fp8_e32 v[58:59], v22
	v_cvt_pk_f32_fp8_sdwa v[60:61], v22 src0_sel:WORD_1
	v_cvt_pk_f32_fp8_e32 v[68:69], v23
	v_cvt_pk_f32_fp8_sdwa v[70:71], v23 src0_sel:WORD_1
	v_lshl_add_u32 v154, s39, 8, v77
	v_or_b32_e32 v138, v138, v34
	v_lshl_add_u64 v[156:157], v[162:163], 0, v[72:73]
	s_waitcnt lgkmcnt(6)
	v_lshlrev_b32_sdwa v72, v141, v146 dst_sel:DWORD dst_unused:UNUSED_PAD src0_sel:DWORD src1_sel:WORD_0
	s_waitcnt vmcnt(5)
	v_cvt_pk_f32_fp8_e32 v[20:21], v24
	v_cvt_pk_f32_fp8_sdwa v[22:23], v24 src0_sel:WORD_1
	v_cvt_pk_f32_fp8_e32 v[56:57], v25
	v_cvt_pk_f32_fp8_sdwa v[24:25], v25 src0_sel:WORD_1
	v_cvt_pk_f32_fp8_e32 v[62:63], v26
	v_cvt_pk_f32_fp8_sdwa v[64:65], v26 src0_sel:WORD_1
	v_cvt_pk_f32_fp8_e32 v[78:79], v27
	v_cvt_pk_f32_fp8_sdwa v[80:81], v27 src0_sel:WORD_1
	ds_read_u16 v175, v173
	ds_read_u16 v179, v173 offset:16
	ds_read_u16 v181, v173 offset:32
	ds_read_u16 v183, v173 offset:48
	ds_read_u16 v185, v173 offset:64
	ds_read_u16 v187, v173 offset:80
	ds_read_u16 v189, v173 offset:96
	ds_read_u16 v191, v173 offset:112
	ds_read_u16 v160, v154
	ds_read_u16 v161, v154 offset:16
	ds_read_u16 v169, v154 offset:32
	ds_read_u16 v174, v154 offset:48
	ds_read_u16 v180, v154 offset:64
	ds_read_u16 v182, v154 offset:80
	ds_read_u16 v184, v154 offset:96
	ds_read_u16 v186, v154 offset:112
	ds_read_u16 v153, v173 offset:128
	ds_read_u16 v188, v154 offset:128
	ds_read_u16 v190, v154 offset:144
	ds_read_u16 v192, v154 offset:160
	ds_read_u16 v193, v154 offset:176
	ds_read_u16 v195, v154 offset:192
	ds_read_u16 v197, v154 offset:208
	ds_read_u16 v199, v154 offset:224
	ds_read_u16 v201, v154 offset:240
	v_lshlrev_b64 v[154:155], 2, v[138:139]
	v_lshl_add_u64 v[138:139], v[138:139], 1, s[64:65]
	v_lshl_add_u64 v[158:159], v[162:163], 0, v[72:73]
	s_waitcnt lgkmcnt(14)
	v_lshlrev_b32_sdwa v72, v141, v151 dst_sel:DWORD dst_unused:UNUSED_PAD src0_sel:DWORD src1_sel:WORD_0
	s_waitcnt vmcnt(4)
	v_cvt_pk_f32_fp8_e32 v[26:27], v12
	v_cvt_pk_f32_fp8_sdwa v[66:67], v12 src0_sel:WORD_1
	v_cvt_pk_f32_fp8_e32 v[82:83], v13
	v_cvt_pk_f32_fp8_sdwa v[12:13], v13 src0_sel:WORD_1
	v_cvt_pk_f32_fp8_e32 v[86:87], v14
	v_cvt_pk_f32_fp8_sdwa v[88:89], v14 src0_sel:WORD_1
	v_cvt_pk_f32_fp8_e32 v[92:93], v15
	v_cvt_pk_f32_fp8_sdwa v[94:95], v15 src0_sel:WORD_1
	ds_read_u16 v146, v173 offset:144
	ds_read_u16 v151, v173 offset:160
	v_lshl_add_u64 v[166:167], s[62:63], 0, v[154:155]
	global_load_dword v203, v[138:139], off
	v_lshlrev_b32_e32 v168, 16, v160
	v_lshlrev_b32_e32 v170, 16, v161
	v_lshl_add_u64 v[138:139], s[60:61], 0, v[154:155]
	global_load_dwordx4 v[154:157], v[156:157], off
	s_nop 0
	global_load_dwordx4 v[158:161], v[158:159], off
	v_lshl_add_u64 v[204:205], v[162:163], 0, v[72:73]
	v_lshlrev_b32_sdwa v72, v141, v152 dst_sel:DWORD dst_unused:UNUSED_PAD src0_sel:DWORD src1_sel:WORD_0
	v_lshlrev_b32_e32 v172, 16, v169
	v_pk_fma_f32 v[36:37], v[36:37], v[168:169], 0 op_sel_hi:[1,0,0]
	v_pk_fma_f32 v[38:39], v[38:39], v[168:169], 0 op_sel_hi:[1,0,0]
	v_pk_fma_f32 v[40:41], v[40:41], v[168:169], 0 op_sel_hi:[1,0,0]
	v_pk_fma_f32 v[28:29], v[28:29], v[168:169], 0 op_sel_hi:[1,0,0]
	v_pk_fma_f32 v[42:43], v[42:43], v[168:169], 0 op_sel_hi:[1,0,0]
	v_pk_fma_f32 v[44:45], v[44:45], v[168:169], 0 op_sel_hi:[1,0,0]
	v_pk_fma_f32 v[48:49], v[48:49], v[168:169], 0 op_sel_hi:[1,0,0]
	v_pk_fma_f32 v[50:51], v[50:51], v[168:169], 0 op_sel_hi:[1,0,0]
	v_lshl_add_u64 v[168:169], v[162:163], 0, v[72:73]
	v_lshlrev_b32_sdwa v72, v141, v147 dst_sel:DWORD dst_unused:UNUSED_PAD src0_sel:DWORD src1_sel:WORD_0
	s_waitcnt vmcnt(6)
	v_cvt_pk_f32_fp8_e32 v[14:15], v16
	v_cvt_pk_f32_fp8_sdwa v[84:85], v16 src0_sel:WORD_1
	v_cvt_pk_f32_fp8_e32 v[90:91], v17
	v_cvt_pk_f32_fp8_sdwa v[16:17], v17 src0_sel:WORD_1
	v_cvt_pk_f32_fp8_e32 v[96:97], v18
	v_cvt_pk_f32_fp8_sdwa v[98:99], v18 src0_sel:WORD_1
	v_cvt_pk_f32_fp8_e32 v[100:101], v19
	v_cvt_pk_f32_fp8_sdwa v[18:19], v19 src0_sel:WORD_1
	ds_read_u16 v152, v173 offset:176
	ds_read_u16 v147, v173 offset:192
	global_load_dwordx2 v[166:167], v[166:167], off
	v_pk_fma_f32 v[30:31], v[30:31], v[170:171], v[36:37] op_sel_hi:[1,0,1]
	v_pk_fma_f32 v[46:47], v[46:47], v[170:171], v[38:39] op_sel_hi:[1,0,1]
	v_pk_fma_f32 v[52:53], v[52:53], v[170:171], v[40:41] op_sel_hi:[1,0,1]
	v_pk_fma_f32 v[28:29], v[54:55], v[170:171], v[28:29] op_sel_hi:[1,0,1]
	v_pk_fma_f32 v[54:55], v[58:59], v[170:171], v[42:43] op_sel_hi:[1,0,1]
	v_pk_fma_f32 v[44:45], v[60:61], v[170:171], v[44:45] op_sel_hi:[1,0,1]
	v_pk_fma_f32 v[48:49], v[68:69], v[170:171], v[48:49] op_sel_hi:[1,0,1]
	v_pk_fma_f32 v[50:51], v[70:71], v[170:171], v[50:51] op_sel_hi:[1,0,1]
	global_load_dwordx4 v[36:39], v[204:205], off
	global_load_dwordx4 v[40:43], v[168:169], off
	v_lshl_add_u64 v[58:59], v[162:163], 0, v[72:73]
	v_lshlrev_b32_sdwa v72, v141, v148 dst_sel:DWORD dst_unused:UNUSED_PAD src0_sel:DWORD src1_sel:WORD_0
	s_waitcnt lgkmcnt(14)
	v_lshlrev_b32_e32 v174, 16, v174
	v_pk_fma_f32 v[20:21], v[20:21], v[172:173], v[30:31] op_sel_hi:[1,0,1]
	v_pk_fma_f32 v[22:23], v[22:23], v[172:173], v[46:47] op_sel_hi:[1,0,1]
	v_pk_fma_f32 v[30:31], v[56:57], v[172:173], v[52:53] op_sel_hi:[1,0,1]
	v_pk_fma_f32 v[24:25], v[24:25], v[172:173], v[28:29] op_sel_hi:[1,0,1]
	v_pk_fma_f32 v[28:29], v[62:63], v[172:173], v[54:55] op_sel_hi:[1,0,1]
	v_pk_fma_f32 v[44:45], v[64:65], v[172:173], v[44:45] op_sel_hi:[1,0,1]
	v_pk_fma_f32 v[46:47], v[78:79], v[172:173], v[48:49] op_sel_hi:[1,0,1]
	v_pk_fma_f32 v[48:49], v[80:81], v[172:173], v[50:51] op_sel_hi:[1,0,1]
	v_lshl_add_u64 v[50:51], v[162:163], 0, v[72:73]
	ds_read_u16 v148, v173 offset:208
	v_lshlrev_b32_sdwa v72, v141, v149 dst_sel:DWORD dst_unused:UNUSED_PAD src0_sel:DWORD src1_sel:WORD_0
	ds_read_u16 v149, v173 offset:224
	v_pk_fma_f32 v[20:21], v[26:27], v[174:175], v[20:21] op_sel_hi:[1,0,1]
	v_pk_fma_f32 v[26:27], v[82:83], v[174:175], v[30:31] op_sel_hi:[1,0,1]
	v_pk_fma_f32 v[12:13], v[12:13], v[174:175], v[24:25] op_sel_hi:[1,0,1]
	v_pk_fma_f32 v[24:25], v[86:87], v[174:175], v[28:29] op_sel_hi:[1,0,1]
	v_pk_fma_f32 v[28:29], v[88:89], v[174:175], v[44:45] op_sel_hi:[1,0,1]
	v_pk_fma_f32 v[30:31], v[92:93], v[174:175], v[46:47] op_sel_hi:[1,0,1]
	v_pk_fma_f32 v[52:53], v[94:95], v[174:175], v[48:49] op_sel_hi:[1,0,1]
	global_load_dwordx4 v[44:47], v[58:59], off
	s_nop 0
	global_load_dwordx4 v[48:51], v[50:51], off
	v_lshlrev_b32_e32 v180, 16, v180
	v_lshl_add_u64 v[54:55], v[162:163], 0, v[72:73]
	v_lshlrev_b32_sdwa v72, v141, v150 dst_sel:DWORD dst_unused:UNUSED_PAD src0_sel:DWORD src1_sel:WORD_0
	ds_read_u16 v150, v173 offset:240
	v_pk_fma_f32 v[12:13], v[16:17], v[180:181], v[12:13] op_sel_hi:[1,0,1]
	v_pk_fma_f32 v[16:17], v[96:97], v[180:181], v[24:25] op_sel_hi:[1,0,1]
	v_pk_fma_f32 v[24:25], v[98:99], v[180:181], v[28:29] op_sel_hi:[1,0,1]
	v_pk_fma_f32 v[18:19], v[18:19], v[180:181], v[52:53] op_sel_hi:[1,0,1]
	v_lshl_add_u64 v[28:29], v[162:163], 0, v[72:73]
	global_load_dwordx4 v[52:55], v[54:55], off
	s_nop 0
	global_load_dwordx4 v[56:59], v[28:29], off
	s_waitcnt vmcnt(12)
	v_cvt_pk_f32_fp8_e32 v[102:103], v4
	v_cvt_pk_f32_fp8_sdwa v[104:105], v4 src0_sel:WORD_1
	v_cvt_pk_f32_fp8_e32 v[106:107], v5
	v_cvt_pk_f32_fp8_sdwa v[4:5], v5 src0_sel:WORD_1
	v_cvt_pk_f32_fp8_e32 v[108:109], v6
	v_cvt_pk_f32_fp8_sdwa v[110:111], v6 src0_sel:WORD_1
	v_cvt_pk_f32_fp8_e32 v[114:115], v7
	v_cvt_pk_f32_fp8_sdwa v[116:117], v7 src0_sel:WORD_1
	s_waitcnt vmcnt(11)
	v_cvt_pk_f32_fp8_e32 v[6:7], v8
	v_cvt_pk_f32_fp8_sdwa v[112:113], v8 src0_sel:WORD_1
	v_cvt_pk_f32_fp8_e32 v[118:119], v9
	v_cvt_pk_f32_fp8_sdwa v[8:9], v9 src0_sel:WORD_1
	v_cvt_pk_f32_fp8_e32 v[120:121], v10
	v_cvt_pk_f32_fp8_sdwa v[122:123], v10 src0_sel:WORD_1
	v_cvt_pk_f32_fp8_e32 v[124:125], v11
	v_cvt_pk_f32_fp8_sdwa v[10:11], v11 src0_sel:WORD_1
	s_waitcnt vmcnt(10)
	v_cvt_pk_f32_fp8_e32 v[126:127], v0
	v_cvt_pk_f32_fp8_sdwa v[128:129], v0 src0_sel:WORD_1
	v_cvt_pk_f32_fp8_e32 v[130:131], v1
	v_cvt_pk_f32_fp8_sdwa v[0:1], v1 src0_sel:WORD_1
	s_and_b32 s18, s3, 0xe00000
	v_pk_fma_f32 v[22:23], v[66:67], v[174:175], v[22:23] op_sel_hi:[1,0,1]
	v_cvt_pk_f32_fp8_e32 v[132:133], v2
	v_cvt_pk_f32_fp8_sdwa v[134:135], v2 src0_sel:WORD_1
	v_cvt_pk_f32_fp8_e32 v[136:137], v3
	v_cvt_pk_f32_fp8_sdwa v[2:3], v3 src0_sel:WORD_1
	v_lshl_add_u64 v[164:165], v[32:33], 0, s[18:19]
	v_lshlrev_b32_e32 v182, 16, v182
	v_pk_fma_f32 v[14:15], v[14:15], v[180:181], v[20:21] op_sel_hi:[1,0,1]
	v_pk_fma_f32 v[20:21], v[84:85], v[180:181], v[22:23] op_sel_hi:[1,0,1]
	v_pk_fma_f32 v[22:23], v[90:91], v[180:181], v[26:27] op_sel_hi:[1,0,1]
	v_pk_fma_f32 v[26:27], v[100:101], v[180:181], v[30:31] op_sel_hi:[1,0,1]
	v_lshlrev_b32_e32 v72, 7, v175
	v_lshlrev_b32_e32 v184, 16, v184
	v_pk_fma_f32 v[4:5], v[4:5], v[182:183], v[12:13] op_sel_hi:[1,0,1]
	v_pk_fma_f32 v[12:13], v[108:109], v[182:183], v[16:17] op_sel_hi:[1,0,1]
	v_pk_fma_f32 v[16:17], v[110:111], v[182:183], v[24:25] op_sel_hi:[1,0,1]
	v_pk_fma_f32 v[24:25], v[114:115], v[182:183], v[26:27] op_sel_hi:[1,0,1]
	v_pk_fma_f32 v[18:19], v[116:117], v[182:183], v[18:19] op_sel_hi:[1,0,1]
	v_lshl_add_u64 v[26:27], v[164:165], 0, v[72:73]
	v_lshlrev_b32_e32 v72, 7, v179
	s_waitcnt lgkmcnt(14)
	v_lshlrev_b32_e32 v186, 16, v186
	v_pk_fma_f32 v[4:5], v[8:9], v[184:185], v[4:5] op_sel_hi:[1,0,1]
	v_pk_fma_f32 v[10:11], v[10:11], v[184:185], v[18:19] op_sel_hi:[1,0,1]
	v_lshl_add_u64 v[18:19], v[164:165], 0, v[72:73]
	v_lshlrev_b32_e32 v72, 7, v181
	v_pk_fma_f32 v[14:15], v[102:103], v[182:183], v[14:15] op_sel_hi:[1,0,1]
	v_pk_fma_f32 v[20:21], v[104:105], v[182:183], v[20:21] op_sel_hi:[1,0,1]
	v_pk_fma_f32 v[22:23], v[106:107], v[182:183], v[22:23] op_sel_hi:[1,0,1]
	v_pk_fma_f32 v[66:67], v[0:1], v[186:187], v[4:5] op_sel_hi:[1,0,1]
	v_lshl_add_u64 v[0:1], v[164:165], 0, v[72:73]
	v_lshlrev_b32_e32 v72, 7, v183
	v_pk_fma_f32 v[6:7], v[6:7], v[184:185], v[14:15] op_sel_hi:[1,0,1]
	v_pk_fma_f32 v[14:15], v[112:113], v[184:185], v[20:21] op_sel_hi:[1,0,1]
	v_pk_fma_f32 v[20:21], v[118:119], v[184:185], v[22:23] op_sel_hi:[1,0,1]
	v_pk_fma_f32 v[8:9], v[120:121], v[184:185], v[12:13] op_sel_hi:[1,0,1]
	v_pk_fma_f32 v[12:13], v[122:123], v[184:185], v[16:17] op_sel_hi:[1,0,1]
	v_pk_fma_f32 v[80:81], v[2:3], v[186:187], v[10:11] op_sel_hi:[1,0,1]
	v_lshl_add_u64 v[2:3], v[164:165], 0, v[72:73]
	v_lshlrev_b32_e32 v72, 7, v185
	v_pk_fma_f32 v[16:17], v[124:125], v[184:185], v[24:25] op_sel_hi:[1,0,1]
	v_pk_fma_f32 v[62:63], v[128:129], v[186:187], v[14:15] op_sel_hi:[1,0,1]
	v_pk_fma_f32 v[64:65], v[130:131], v[186:187], v[20:21] op_sel_hi:[1,0,1]
	v_pk_fma_f32 v[70:71], v[134:135], v[186:187], v[12:13] op_sel_hi:[1,0,1]
	global_load_dwordx4 v[28:31], v[26:27], off
	global_load_dwordx4 v[20:23], v[18:19], off
	s_nop 0
	global_load_dwordx4 v[24:27], v[0:1], off
	global_load_dwordx4 v[12:15], v[2:3], off
	v_lshl_add_u64 v[0:1], v[164:165], 0, v[72:73]
	v_lshlrev_b32_e32 v72, 7, v187
	v_lshl_add_u64 v[2:3], v[164:165], 0, v[72:73]
	v_lshlrev_b32_e32 v72, 7, v189
	v_pk_fma_f32 v[60:61], v[126:127], v[186:187], v[6:7] op_sel_hi:[1,0,1]
	v_pk_fma_f32 v[78:79], v[136:137], v[186:187], v[16:17] op_sel_hi:[1,0,1]
	global_load_dwordx4 v[16:19], v[0:1], off
	global_load_dwordx4 v[4:7], v[2:3], off
	v_lshl_add_u64 v[0:1], v[164:165], 0, v[72:73]
	v_lshlrev_b32_e32 v72, 7, v191
	v_lshl_add_u64 v[2:3], v[164:165], 0, v[72:73]
	v_pk_fma_f32 v[68:69], v[132:133], v[186:187], v[8:9] op_sel_hi:[1,0,1]
	global_load_dwordx4 v[8:11], v[0:1], off
	s_nop 0
	global_load_dwordx4 v[0:3], v[2:3], off
	s_waitcnt vmcnt(16)
	v_cvt_pk_f32_fp8_e32 v[82:83], v154
	v_cvt_pk_f32_fp8_sdwa v[84:85], v154 src0_sel:WORD_1
	v_cvt_pk_f32_fp8_e32 v[86:87], v155
	v_cvt_pk_f32_fp8_sdwa v[88:89], v155 src0_sel:WORD_1
	v_cvt_pk_f32_fp8_e32 v[90:91], v156
	v_cvt_pk_f32_fp8_sdwa v[92:93], v156 src0_sel:WORD_1
	v_cvt_pk_f32_fp8_e32 v[94:95], v157
	v_cvt_pk_f32_fp8_sdwa v[96:97], v157 src0_sel:WORD_1
	s_waitcnt vmcnt(15)
	v_cvt_pk_f32_fp8_e32 v[100:101], v158
	v_cvt_pk_f32_fp8_sdwa v[102:103], v158 src0_sel:WORD_1
	v_cvt_pk_f32_fp8_e32 v[104:105], v159
	v_cvt_pk_f32_fp8_sdwa v[106:107], v159 src0_sel:WORD_1
	v_cvt_pk_f32_fp8_e32 v[108:109], v160
	v_cvt_pk_f32_fp8_sdwa v[110:111], v160 src0_sel:WORD_1
	v_cvt_pk_f32_fp8_e32 v[112:113], v161
	v_cvt_pk_f32_fp8_sdwa v[114:115], v161 src0_sel:WORD_1
	s_waitcnt vmcnt(13)
	v_cvt_pk_f32_fp8_e32 v[116:117], v36
	v_cvt_pk_f32_fp8_sdwa v[118:119], v36 src0_sel:WORD_1
	v_cvt_pk_f32_fp8_e32 v[120:121], v37
	v_cvt_pk_f32_fp8_sdwa v[36:37], v37 src0_sel:WORD_1
	v_cvt_pk_f32_fp8_e32 v[122:123], v38
	v_cvt_pk_f32_fp8_sdwa v[124:125], v38 src0_sel:WORD_1
	v_cvt_pk_f32_fp8_e32 v[126:127], v39
	v_cvt_pk_f32_fp8_sdwa v[38:39], v39 src0_sel:WORD_1
	v_lshlrev_b32_e32 v188, 16, v188
	s_waitcnt vmcnt(12)
	v_cvt_pk_f32_fp8_e32 v[128:129], v40
	v_cvt_pk_f32_fp8_sdwa v[130:131], v40 src0_sel:WORD_1
	v_cvt_pk_f32_fp8_e32 v[132:133], v41
	v_cvt_pk_f32_fp8_sdwa v[40:41], v41 src0_sel:WORD_1
	v_cvt_pk_f32_fp8_e32 v[134:135], v42
	v_cvt_pk_f32_fp8_sdwa v[136:137], v42 src0_sel:WORD_1
	v_cvt_pk_f32_fp8_e32 v[154:155], v43
	v_cvt_pk_f32_fp8_sdwa v[42:43], v43 src0_sel:WORD_1
	s_waitcnt lgkmcnt(13)
	v_lshlrev_b32_e32 v190, 16, v190
	v_pk_fma_f32 v[60:61], v[82:83], v[188:189], v[60:61] op_sel_hi:[1,0,1]
	v_pk_fma_f32 v[62:63], v[84:85], v[188:189], v[62:63] op_sel_hi:[1,0,1]
	v_pk_fma_f32 v[64:65], v[86:87], v[188:189], v[64:65] op_sel_hi:[1,0,1]
	v_pk_fma_f32 v[66:67], v[88:89], v[188:189], v[66:67] op_sel_hi:[1,0,1]
	v_pk_fma_f32 v[68:69], v[90:91], v[188:189], v[68:69] op_sel_hi:[1,0,1]
	v_pk_fma_f32 v[70:71], v[92:93], v[188:189], v[70:71] op_sel_hi:[1,0,1]
	v_pk_fma_f32 v[78:79], v[94:95], v[188:189], v[78:79] op_sel_hi:[1,0,1]
	v_pk_fma_f32 v[80:81], v[96:97], v[188:189], v[80:81] op_sel_hi:[1,0,1]
	s_waitcnt vmcnt(11)
	v_cvt_pk_f32_fp8_e32 v[82:83], v44
	v_cvt_pk_f32_fp8_sdwa v[84:85], v44 src0_sel:WORD_1
	v_cvt_pk_f32_fp8_e32 v[86:87], v45
	v_cvt_pk_f32_fp8_sdwa v[44:45], v45 src0_sel:WORD_1
	v_cvt_pk_f32_fp8_e32 v[88:89], v46
	v_cvt_pk_f32_fp8_sdwa v[90:91], v46 src0_sel:WORD_1
	v_cvt_pk_f32_fp8_e32 v[92:93], v47
	v_cvt_pk_f32_fp8_sdwa v[46:47], v47 src0_sel:WORD_1
	s_waitcnt lgkmcnt(12)
	v_lshlrev_b32_e32 v192, 16, v192
	v_pk_fma_f32 v[60:61], v[100:101], v[190:191], v[60:61] op_sel_hi:[1,0,1]
	v_pk_fma_f32 v[62:63], v[102:103], v[190:191], v[62:63] op_sel_hi:[1,0,1]
	v_pk_fma_f32 v[64:65], v[104:105], v[190:191], v[64:65] op_sel_hi:[1,0,1]
	v_pk_fma_f32 v[66:67], v[106:107], v[190:191], v[66:67] op_sel_hi:[1,0,1]
	v_pk_fma_f32 v[68:69], v[108:109], v[190:191], v[68:69] op_sel_hi:[1,0,1]
	v_pk_fma_f32 v[70:71], v[110:111], v[190:191], v[70:71] op_sel_hi:[1,0,1]
	v_pk_fma_f32 v[78:79], v[112:113], v[190:191], v[78:79] op_sel_hi:[1,0,1]
	v_pk_fma_f32 v[80:81], v[114:115], v[190:191], v[80:81] op_sel_hi:[1,0,1]
	s_waitcnt vmcnt(10)
	v_cvt_pk_f32_fp8_e32 v[94:95], v48
	v_cvt_pk_f32_fp8_sdwa v[96:97], v48 src0_sel:WORD_1
	v_cvt_pk_f32_fp8_e32 v[100:101], v49
	v_cvt_pk_f32_fp8_sdwa v[48:49], v49 src0_sel:WORD_1
	v_cvt_pk_f32_fp8_e32 v[102:103], v50
	v_cvt_pk_f32_fp8_sdwa v[104:105], v50 src0_sel:WORD_1
	v_cvt_pk_f32_fp8_e32 v[106:107], v51
	v_cvt_pk_f32_fp8_sdwa v[50:51], v51 src0_sel:WORD_1
	s_waitcnt lgkmcnt(11)
	v_lshlrev_b32_e32 v194, 16, v193
	v_pk_fma_f32 v[60:61], v[116:117], v[192:193], v[60:61] op_sel_hi:[1,0,1]
	v_pk_fma_f32 v[62:63], v[118:119], v[192:193], v[62:63] op_sel_hi:[1,0,1]
	v_pk_fma_f32 v[64:65], v[120:121], v[192:193], v[64:65] op_sel_hi:[1,0,1]
	v_pk_fma_f32 v[36:37], v[36:37], v[192:193], v[66:67] op_sel_hi:[1,0,1]
	v_pk_fma_f32 v[66:67], v[122:123], v[192:193], v[68:69] op_sel_hi:[1,0,1]
	v_pk_fma_f32 v[68:69], v[124:125], v[192:193], v[70:71] op_sel_hi:[1,0,1]
	v_pk_fma_f32 v[70:71], v[126:127], v[192:193], v[78:79] op_sel_hi:[1,0,1]
	v_pk_fma_f32 v[38:39], v[38:39], v[192:193], v[80:81] op_sel_hi:[1,0,1]
	s_waitcnt vmcnt(9)
	v_cvt_pk_f32_fp8_e32 v[78:79], v52
	v_cvt_pk_f32_fp8_sdwa v[80:81], v52 src0_sel:WORD_1
	v_cvt_pk_f32_fp8_e32 v[108:109], v53
	v_cvt_pk_f32_fp8_sdwa v[52:53], v53 src0_sel:WORD_1
	v_cvt_pk_f32_fp8_e32 v[110:111], v54
	v_cvt_pk_f32_fp8_sdwa v[112:113], v54 src0_sel:WORD_1
	v_cvt_pk_f32_fp8_e32 v[114:115], v55
	v_cvt_pk_f32_fp8_sdwa v[54:55], v55 src0_sel:WORD_1
	s_waitcnt lgkmcnt(10)
	v_lshlrev_b32_e32 v196, 16, v195
	v_pk_fma_f32 v[60:61], v[128:129], v[194:195], v[60:61] op_sel_hi:[1,0,1]
	v_pk_fma_f32 v[62:63], v[130:131], v[194:195], v[62:63] op_sel_hi:[1,0,1]
	v_pk_fma_f32 v[64:65], v[132:133], v[194:195], v[64:65] op_sel_hi:[1,0,1]
	v_pk_fma_f32 v[36:37], v[40:41], v[194:195], v[36:37] op_sel_hi:[1,0,1]
	v_pk_fma_f32 v[40:41], v[134:135], v[194:195], v[66:67] op_sel_hi:[1,0,1]
	v_pk_fma_f32 v[66:67], v[136:137], v[194:195], v[68:69] op_sel_hi:[1,0,1]
	v_pk_fma_f32 v[68:69], v[154:155], v[194:195], v[70:71] op_sel_hi:[1,0,1]
	v_pk_fma_f32 v[38:39], v[42:43], v[194:195], v[38:39] op_sel_hi:[1,0,1]
	s_waitcnt vmcnt(8)
	v_cvt_pk_f32_fp8_e32 v[42:43], v56
	v_cvt_pk_f32_fp8_sdwa v[70:71], v56 src0_sel:WORD_1
	v_cvt_pk_f32_fp8_e32 v[116:117], v57
	v_cvt_pk_f32_fp8_sdwa v[56:57], v57 src0_sel:WORD_1
	v_cvt_pk_f32_fp8_e32 v[118:119], v58
	v_cvt_pk_f32_fp8_sdwa v[120:121], v58 src0_sel:WORD_1
	v_cvt_pk_f32_fp8_e32 v[122:123], v59
	v_cvt_pk_f32_fp8_sdwa v[58:59], v59 src0_sel:WORD_1
	s_waitcnt lgkmcnt(9)
	v_lshlrev_b32_e32 v198, 16, v197
	v_pk_fma_f32 v[60:61], v[82:83], v[196:197], v[60:61] op_sel_hi:[1,0,1]
	v_pk_fma_f32 v[62:63], v[84:85], v[196:197], v[62:63] op_sel_hi:[1,0,1]
	v_pk_fma_f32 v[64:65], v[86:87], v[196:197], v[64:65] op_sel_hi:[1,0,1]
	v_pk_fma_f32 v[36:37], v[44:45], v[196:197], v[36:37] op_sel_hi:[1,0,1]
	v_pk_fma_f32 v[40:41], v[88:89], v[196:197], v[40:41] op_sel_hi:[1,0,1]
	v_pk_fma_f32 v[44:45], v[90:91], v[196:197], v[66:67] op_sel_hi:[1,0,1]
	v_pk_fma_f32 v[66:67], v[92:93], v[196:197], v[68:69] op_sel_hi:[1,0,1]
	v_pk_fma_f32 v[38:39], v[46:47], v[196:197], v[38:39] op_sel_hi:[1,0,1]
	s_waitcnt lgkmcnt(8)
	v_lshlrev_b32_e32 v200, 16, v199
	v_pk_fma_f32 v[46:47], v[94:95], v[198:199], v[60:61] op_sel_hi:[1,0,1]
	v_pk_fma_f32 v[60:61], v[96:97], v[198:199], v[62:63] op_sel_hi:[1,0,1]
	v_pk_fma_f32 v[62:63], v[100:101], v[198:199], v[64:65] op_sel_hi:[1,0,1]
	v_pk_fma_f32 v[36:37], v[48:49], v[198:199], v[36:37] op_sel_hi:[1,0,1]
	v_pk_fma_f32 v[40:41], v[102:103], v[198:199], v[40:41] op_sel_hi:[1,0,1]
	v_pk_fma_f32 v[44:45], v[104:105], v[198:199], v[44:45] op_sel_hi:[1,0,1]
	v_pk_fma_f32 v[48:49], v[106:107], v[198:199], v[66:67] op_sel_hi:[1,0,1]
	v_pk_fma_f32 v[38:39], v[50:51], v[198:199], v[38:39] op_sel_hi:[1,0,1]
	s_waitcnt lgkmcnt(7)
	v_lshlrev_b32_e32 v202, 16, v201
	v_pk_fma_f32 v[46:47], v[78:79], v[200:201], v[46:47] op_sel_hi:[1,0,1]
	v_pk_fma_f32 v[50:51], v[80:81], v[200:201], v[60:61] op_sel_hi:[1,0,1]
	v_pk_fma_f32 v[60:61], v[108:109], v[200:201], v[62:63] op_sel_hi:[1,0,1]
	v_pk_fma_f32 v[36:37], v[52:53], v[200:201], v[36:37] op_sel_hi:[1,0,1]
	v_pk_fma_f32 v[40:41], v[110:111], v[200:201], v[40:41] op_sel_hi:[1,0,1]
	v_pk_fma_f32 v[44:45], v[112:113], v[200:201], v[44:45] op_sel_hi:[1,0,1]
	v_pk_fma_f32 v[48:49], v[114:115], v[200:201], v[48:49] op_sel_hi:[1,0,1]
	v_pk_fma_f32 v[38:39], v[54:55], v[200:201], v[38:39] op_sel_hi:[1,0,1]
	v_pk_fma_f32 v[42:43], v[42:43], v[202:203], v[46:47] op_sel_hi:[1,0,1]
	v_pk_fma_f32 v[46:47], v[70:71], v[202:203], v[50:51] op_sel_hi:[1,0,1]
	v_pk_fma_f32 v[50:51], v[116:117], v[202:203], v[60:61] op_sel_hi:[1,0,1]
	v_pk_fma_f32 v[36:37], v[56:57], v[202:203], v[36:37] op_sel_hi:[1,0,1]
	v_pk_fma_f32 v[40:41], v[118:119], v[202:203], v[40:41] op_sel_hi:[1,0,1]
	v_pk_fma_f32 v[44:45], v[120:121], v[202:203], v[44:45] op_sel_hi:[1,0,1]
	v_pk_fma_f32 v[48:49], v[122:123], v[202:203], v[48:49] op_sel_hi:[1,0,1]
	v_pk_fma_f32 v[38:39], v[58:59], v[202:203], v[38:39] op_sel_hi:[1,0,1]
	v_cndmask_b32_e64 v52, v42, v40, s[4:5]
	v_cndmask_b32_e64 v53, v43, v41, s[4:5]
	v_cndmask_b32_e64 v41, v41, v43, s[4:5]
	v_cndmask_b32_e64 v40, v40, v42, s[4:5]
	v_cndmask_b32_e64 v54, v46, v44, s[4:5]
	v_cndmask_b32_e64 v55, v47, v45, s[4:5]
	v_cndmask_b32_e64 v43, v45, v47, s[4:5]
	v_cndmask_b32_e64 v42, v44, v46, s[4:5]
	v_cndmask_b32_e64 v56, v50, v48, s[4:5]
	v_cndmask_b32_e64 v57, v51, v49, s[4:5]
	v_cndmask_b32_e64 v45, v49, v51, s[4:5]
	v_cndmask_b32_e64 v44, v48, v50, s[4:5]
	v_cndmask_b32_e64 v50, v36, v38, s[4:5]
	v_cndmask_b32_e64 v51, v37, v39, s[4:5]
	v_cndmask_b32_e64 v37, v39, v37, s[4:5]
	v_cndmask_b32_e64 v36, v38, v36, s[4:5]
	ds_bpermute_b32 v38, v35, v52
	ds_bpermute_b32 v39, v35, v53
	ds_bpermute_b32 v46, v35, v54
	ds_bpermute_b32 v47, v35, v55
	ds_bpermute_b32 v48, v35, v56
	ds_bpermute_b32 v49, v35, v57
	ds_bpermute_b32 v50, v35, v50
	ds_bpermute_b32 v51, v35, v51
	s_waitcnt lgkmcnt(6)
	v_pk_add_f32 v[38:39], v[40:41], v[38:39]
	s_waitcnt lgkmcnt(4)
	v_pk_add_f32 v[40:41], v[42:43], v[46:47]
	s_waitcnt lgkmcnt(2)
	v_pk_add_f32 v[42:43], v[44:45], v[48:49]
	v_lshlrev_b32_e32 v98, 16, v203
	s_waitcnt lgkmcnt(0)
	v_pk_add_f32 v[36:37], v[36:37], v[50:51]
	v_cndmask_b32_e32 v44, v38, v42, vcc
	v_cndmask_b32_e32 v45, v39, v43, vcc
	v_cndmask_b32_e32 v39, v43, v39, vcc
	v_cndmask_b32_e32 v38, v42, v38, vcc
	v_cndmask_b32_e32 v42, v40, v36, vcc
	v_cndmask_b32_e32 v43, v41, v37, vcc
	v_cndmask_b32_e32 v37, v37, v41, vcc
	v_cndmask_b32_e32 v36, v36, v40, vcc
	ds_bpermute_b32 v40, v144, v44
	ds_bpermute_b32 v41, v144, v45
	ds_bpermute_b32 v42, v144, v42
	ds_bpermute_b32 v43, v144, v43
	v_and_b32_e32 v99, 0xffff0000, v203
	s_add_i32 s7, s41, 1
	s_waitcnt lgkmcnt(2)
	v_pk_add_f32 v[38:39], v[38:39], v[40:41]
	s_addk_i32 s6, 0x80
	s_waitcnt lgkmcnt(0)
	v_pk_add_f32 v[36:37], v[36:37], v[42:43]
	s_add_i32 s3, s3, 0x10000
	v_cndmask_b32_e64 v40, v38, v36, s[0:1]
	v_cndmask_b32_e64 v41, v39, v37, s[0:1]
	v_cndmask_b32_e64 v37, v37, v39, s[0:1]
	v_cndmask_b32_e64 v36, v36, v38, s[0:1]
	v_mov_b32_dpp v38, v40 row_ror:8 row_mask:0xf bank_mask:0xf bound_ctrl:1
	v_mov_b32_dpp v39, v41 row_ror:8 row_mask:0xf bank_mask:0xf bound_ctrl:1
	v_pk_add_f32 v[166:167], v[166:167], s[100:101] op_sel_hi:[1,0] neg_lo:[0,1] neg_hi:[0,1]
	s_nop 0
	v_pk_mul_f32 v[166:167], v[166:167], s[100:101] op_sel:[0,1]
	s_nop 0
	v_pk_fma_f32 v[166:167], v[246:247], v[166:167], v[248:249]
	s_nop 0
	v_pk_fma_f32 v[98:99], v[166:167], s[58:59], v[98:99] op_sel_hi:[1,0,1]
	v_pk_add_f32 v[36:37], v[36:37], v[38:39]
	s_mov_b32 s41, s7
	s_cmpk_eq_i32 s7, 0x100
	v_pk_add_f32 v[36:37], v[98:99], v[36:37]
	global_store_dwordx2 v[138:139], v[36:37], off
	s_cbranch_scc0 .LBB0_1139
	s_waitcnt vmcnt(0)
	s_barrier
	v_lshlrev_b64 v[0:1], 12, v[74:75]
	v_lshl_add_u64 v[0:1], s[60:61], 0, v[0:1]
	v_mov_b32_e32 v77, v73
	v_lshl_add_u64 v[64:65], v[0:1], 0, v[76:77]
	v_lshl_add_u64 v[66:67], s[90:91], 0, v[76:77]
	v_lshl_add_u64 v[68:69], s[68:69], 0, v[76:77]
	s_mov_b64 s[100:101], 0x1000
	v_lshl_add_u64 v[64:65], v[64:65], 0, s[100:101]
	global_load_dwordx4 v[206:209], v[66:67], off
	global_load_dwordx4 v[210:213], v[66:67], off offset:1024
	global_load_dwordx4 v[214:217], v[66:67], off offset:2048
	global_load_dwordx4 v[218:221], v[66:67], off offset:3072
	global_load_dwordx4 v[222:225], v[68:69], off
	global_load_dwordx4 v[226:229], v[68:69], off offset:1024
	global_load_dwordx4 v[230:233], v[68:69], off offset:2048
	global_load_dwordx4 v[234:237], v[68:69], off offset:3072
	global_load_dwordx4 v[0:3], v[64:65], off offset:-4096
	global_load_dwordx4 v[4:7], v[64:65], off offset:-3072
	global_load_dwordx4 v[8:11], v[64:65], off offset:-2048
	global_load_dwordx4 v[12:15], v[64:65], off offset:-1024
	global_load_dwordx4 v[40:43], v[66:67], off
	global_load_dwordx4 v[40:43], v[66:67], off
	global_load_dwordx4 v[40:43], v[66:67], off
	global_load_dwordx4 v[40:43], v[66:67], off
	s_mov_b32 s0, 0
.Lln2_pair:
	global_load_dwordx4 v[16:19], v[64:65], off
	global_load_dwordx4 v[20:23], v[64:65], off offset:1024
	global_load_dwordx4 v[24:27], v[64:65], off offset:2048
	global_load_dwordx4 v[28:31], v[64:65], off offset:3072
	s_waitcnt vmcnt(8)
	v_pk_add_f32 v[32:33], v[0:1], v[2:3]
	v_pk_add_f32 v[34:35], v[4:5], v[6:7]
	v_pk_add_f32 v[36:37], v[8:9], v[10:11]
	v_pk_add_f32 v[38:39], v[12:13], v[14:15]
	v_pk_add_f32 v[32:33], v[32:33], v[34:35]
	v_pk_add_f32 v[36:37], v[36:37], v[38:39]
	s_nop 0
	v_pk_add_f32 v[32:33], v[32:33], v[36:37]
	s_nop 0
	v_add_f32_e32 v32, v32, v33
	s_nop 1
	v_add_f32_dpp v32, v32, v32 quad_perm:[1,0,3,2] row_mask:0xf bank_mask:0xf bound_ctrl:1
	s_nop 1
	v_add_f32_dpp v32, v32, v32 quad_perm:[2,3,0,1] row_mask:0xf bank_mask:0xf bound_ctrl:1
	s_nop 1
	v_add_f32_dpp v32, v32, v32 row_ror:4 row_mask:0xf bank_mask:0xf bound_ctrl:1
	s_nop 1
	v_add_f32_dpp v32, v32, v32 row_ror:8 row_mask:0xf bank_mask:0xf bound_ctrl:1
	s_nop 1
	v_add_f32_dpp v32, v32, v32 row_bcast:15 row_mask:0xa bank_mask:0xf
	s_nop 1
	v_add_f32_dpp v32, v32, v32 row_bcast:31 row_mask:0xc bank_mask:0xf
	s_nop 0
	v_readlane_b32 s98, v32, 63
	s_nop 1
	v_mov_b32_e32 v34, s98
	v_mul_f32_e32 v34, 0x3a800000, v34
	v_pk_add_f32 v[0:1], v[0:1], v[34:35] op_sel_hi:[1,0] neg_lo:[0,1] neg_hi:[0,1]
	v_pk_add_f32 v[2:3], v[2:3], v[34:35] op_sel_hi:[1,0] neg_lo:[0,1] neg_hi:[0,1]
	v_pk_add_f32 v[4:5], v[4:5], v[34:35] op_sel_hi:[1,0] neg_lo:[0,1] neg_hi:[0,1]
	v_pk_add_f32 v[6:7], v[6:7], v[34:35] op_sel_hi:[1,0] neg_lo:[0,1] neg_hi:[0,1]
	v_pk_add_f32 v[8:9], v[8:9], v[34:35] op_sel_hi:[1,0] neg_lo:[0,1] neg_hi:[0,1]
	v_pk_add_f32 v[10:11], v[10:11], v[34:35] op_sel_hi:[1,0] neg_lo:[0,1] neg_hi:[0,1]
	v_pk_add_f32 v[12:13], v[12:13], v[34:35] op_sel_hi:[1,0] neg_lo:[0,1] neg_hi:[0,1]
	v_pk_add_f32 v[14:15], v[14:15], v[34:35] op_sel_hi:[1,0] neg_lo:[0,1] neg_hi:[0,1]
	v_pk_mul_f32 v[36:37], v[0:1], v[0:1]
	v_pk_mul_f32 v[38:39], v[2:3], v[2:3]
	v_pk_fma_f32 v[36:37], v[4:5], v[4:5], v[36:37]
	v_pk_fma_f32 v[38:39], v[6:7], v[6:7], v[38:39]
	v_pk_fma_f32 v[36:37], v[8:9], v[8:9], v[36:37]
	v_pk_fma_f32 v[38:39], v[10:11], v[10:11], v[38:39]
	v_pk_fma_f32 v[36:37], v[12:13], v[12:13], v[36:37]
	v_pk_fma_f32 v[38:39], v[14:15], v[14:15], v[38:39]
	s_nop 0
	v_pk_add_f32 v[36:37], v[36:37], v[38:39]
	s_nop 0
	v_add_f32_e32 v36, v36, v37
	s_nop 1
	v_add_f32_dpp v36, v36, v36 quad_perm:[1,0,3,2] row_mask:0xf bank_mask:0xf bound_ctrl:1
	s_nop 1
	v_add_f32_dpp v36, v36, v36 quad_perm:[2,3,0,1] row_mask:0xf bank_mask:0xf bound_ctrl:1
	s_nop 1
	v_add_f32_dpp v36, v36, v36 row_ror:4 row_mask:0xf bank_mask:0xf bound_ctrl:1
	s_nop 1
	v_add_f32_dpp v36, v36, v36 row_ror:8 row_mask:0xf bank_mask:0xf bound_ctrl:1
	s_nop 1
	v_add_f32_dpp v36, v36, v36 row_bcast:15 row_mask:0xa bank_mask:0xf
	s_nop 1
	v_add_f32_dpp v36, v36, v36 row_bcast:31 row_mask:0xc bank_mask:0xf
	s_nop 0
	v_readlane_b32 s99, v36, 63
	s_nop 1
	v_mov_b32_e32 v38, s99
	v_fmamk_f32 v38, v38, 0x3a800000, v140
	v_rsq_f32_e32 v38, v38
	s_nop 0
	v_pk_mul_f32 v[0:1], v[0:1], v[38:39] op_sel_hi:[1,0]
	v_pk_mul_f32 v[2:3], v[2:3], v[38:39] op_sel_hi:[1,0]
	v_pk_mul_f32 v[4:5], v[4:5], v[38:39] op_sel_hi:[1,0]
	v_pk_mul_f32 v[6:7], v[6:7], v[38:39] op_sel_hi:[1,0]
	v_pk_mul_f32 v[8:9], v[8:9], v[38:39] op_sel_hi:[1,0]
	v_pk_mul_f32 v[10:11], v[10:11], v[38:39] op_sel_hi:[1,0]
	v_pk_mul_f32 v[12:13], v[12:13], v[38:39] op_sel_hi:[1,0]
	v_pk_mul_f32 v[14:15], v[14:15], v[38:39] op_sel_hi:[1,0]
	v_pk_fma_f32 v[0:1], v[206:207], v[0:1], v[222:223]
	v_pk_fma_f32 v[2:3], v[208:209], v[2:3], v[224:225]
	v_pk_fma_f32 v[4:5], v[210:211], v[4:5], v[226:227]
	v_pk_fma_f32 v[6:7], v[212:213], v[6:7], v[228:229]
	v_pk_fma_f32 v[8:9], v[214:215], v[8:9], v[230:231]
	v_pk_fma_f32 v[10:11], v[216:217], v[10:11], v[232:233]
	v_pk_fma_f32 v[12:13], v[218:219], v[12:13], v[234:235]
	v_pk_fma_f32 v[14:15], v[220:221], v[14:15], v[236:237]
	s_nop 0
	global_store_dwordx4 v[64:65], v[0:3], off offset:-4096
	global_store_dwordx4 v[64:65], v[4:7], off offset:-3072
	global_store_dwordx4 v[64:65], v[8:11], off offset:-2048
	global_store_dwordx4 v[64:65], v[12:15], off offset:-1024
	s_movk_i32 s100, 0x2000
	s_cmp_lt_u32 s0, 15
	s_cselect_b32 s100, s100, 0x1000
	s_mov_b32 s101, 0
	v_lshl_add_u64 v[58:59], v[64:65], 0, s[100:101]
	global_load_dwordx4 v[0:3], v[58:59], off offset:-4096
	global_load_dwordx4 v[4:7], v[58:59], off offset:-3072
	global_load_dwordx4 v[8:11], v[58:59], off offset:-2048
	global_load_dwordx4 v[12:15], v[58:59], off offset:-1024
	s_waitcnt vmcnt(8)
	v_pk_add_f32 v[32:33], v[16:17], v[18:19]
	v_pk_add_f32 v[34:35], v[20:21], v[22:23]
	v_pk_add_f32 v[36:37], v[24:25], v[26:27]
	v_pk_add_f32 v[38:39], v[28:29], v[30:31]
	v_pk_add_f32 v[32:33], v[32:33], v[34:35]
	v_pk_add_f32 v[36:37], v[36:37], v[38:39]
	s_nop 0
	v_pk_add_f32 v[32:33], v[32:33], v[36:37]
	s_nop 0
	v_add_f32_e32 v32, v32, v33
	s_nop 1
	v_add_f32_dpp v32, v32, v32 quad_perm:[1,0,3,2] row_mask:0xf bank_mask:0xf bound_ctrl:1
	s_nop 1
	v_add_f32_dpp v32, v32, v32 quad_perm:[2,3,0,1] row_mask:0xf bank_mask:0xf bound_ctrl:1
	s_nop 1
	v_add_f32_dpp v32, v32, v32 row_ror:4 row_mask:0xf bank_mask:0xf bound_ctrl:1
	s_nop 1
	v_add_f32_dpp v32, v32, v32 row_ror:8 row_mask:0xf bank_mask:0xf bound_ctrl:1
	s_nop 1
	v_add_f32_dpp v32, v32, v32 row_bcast:15 row_mask:0xa bank_mask:0xf
	s_nop 1
	v_add_f32_dpp v32, v32, v32 row_bcast:31 row_mask:0xc bank_mask:0xf
	s_nop 0
	v_readlane_b32 s98, v32, 63
	s_nop 1
	v_mov_b32_e32 v34, s98
	v_mul_f32_e32 v34, 0x3a800000, v34
	v_pk_add_f32 v[16:17], v[16:17], v[34:35] op_sel_hi:[1,0] neg_lo:[0,1] neg_hi:[0,1]
	v_pk_add_f32 v[18:19], v[18:19], v[34:35] op_sel_hi:[1,0] neg_lo:[0,1] neg_hi:[0,1]
	v_pk_add_f32 v[20:21], v[20:21], v[34:35] op_sel_hi:[1,0] neg_lo:[0,1] neg_hi:[0,1]
	v_pk_add_f32 v[22:23], v[22:23], v[34:35] op_sel_hi:[1,0] neg_lo:[0,1] neg_hi:[0,1]
	v_pk_add_f32 v[24:25], v[24:25], v[34:35] op_sel_hi:[1,0] neg_lo:[0,1] neg_hi:[0,1]
	v_pk_add_f32 v[26:27], v[26:27], v[34:35] op_sel_hi:[1,0] neg_lo:[0,1] neg_hi:[0,1]
	v_pk_add_f32 v[28:29], v[28:29], v[34:35] op_sel_hi:[1,0] neg_lo:[0,1] neg_hi:[0,1]
	v_pk_add_f32 v[30:31], v[30:31], v[34:35] op_sel_hi:[1,0] neg_lo:[0,1] neg_hi:[0,1]
	v_pk_mul_f32 v[36:37], v[16:17], v[16:17]
	v_pk_mul_f32 v[38:39], v[18:19], v[18:19]
	v_pk_fma_f32 v[36:37], v[20:21], v[20:21], v[36:37]
	v_pk_fma_f32 v[38:39], v[22:23], v[22:23], v[38:39]
	v_pk_fma_f32 v[36:37], v[24:25], v[24:25], v[36:37]
	v_pk_fma_f32 v[38:39], v[26:27], v[26:27], v[38:39]
	v_pk_fma_f32 v[36:37], v[28:29], v[28:29], v[36:37]
	v_pk_fma_f32 v[38:39], v[30:31], v[30:31], v[38:39]
	s_nop 0
	v_pk_add_f32 v[36:37], v[36:37], v[38:39]
	s_nop 0
	v_add_f32_e32 v36, v36, v37
	s_nop 1
	v_add_f32_dpp v36, v36, v36 quad_perm:[1,0,3,2] row_mask:0xf bank_mask:0xf bound_ctrl:1
	s_nop 1
	v_add_f32_dpp v36, v36, v36 quad_perm:[2,3,0,1] row_mask:0xf bank_mask:0xf bound_ctrl:1
	s_nop 1
	v_add_f32_dpp v36, v36, v36 row_ror:4 row_mask:0xf bank_mask:0xf bound_ctrl:1
	s_nop 1
	v_add_f32_dpp v36, v36, v36 row_ror:8 row_mask:0xf bank_mask:0xf bound_ctrl:1
	s_nop 1
	v_add_f32_dpp v36, v36, v36 row_bcast:15 row_mask:0xa bank_mask:0xf
	s_nop 1
	v_add_f32_dpp v36, v36, v36 row_bcast:31 row_mask:0xc bank_mask:0xf
	s_nop 0
	v_readlane_b32 s99, v36, 63
	s_nop 1
	v_mov_b32_e32 v38, s99
	v_fmamk_f32 v38, v38, 0x3a800000, v140
	v_rsq_f32_e32 v38, v38
	s_nop 0
	v_pk_mul_f32 v[16:17], v[16:17], v[38:39] op_sel_hi:[1,0]
	v_pk_mul_f32 v[18:19], v[18:19], v[38:39] op_sel_hi:[1,0]
	v_pk_mul_f32 v[20:21], v[20:21], v[38:39] op_sel_hi:[1,0]
	v_pk_mul_f32 v[22:23], v[22:23], v[38:39] op_sel_hi:[1,0]
	v_pk_mul_f32 v[24:25], v[24:25], v[38:39] op_sel_hi:[1,0]
	v_pk_mul_f32 v[26:27], v[26:27], v[38:39] op_sel_hi:[1,0]
	v_pk_mul_f32 v[28:29], v[28:29], v[38:39] op_sel_hi:[1,0]
	v_pk_mul_f32 v[30:31], v[30:31], v[38:39] op_sel_hi:[1,0]
	v_pk_fma_f32 v[16:17], v[206:207], v[16:17], v[222:223]
	v_pk_fma_f32 v[18:19], v[208:209], v[18:19], v[224:225]
	v_pk_fma_f32 v[20:21], v[210:211], v[20:21], v[226:227]
	v_pk_fma_f32 v[22:23], v[212:213], v[22:23], v[228:229]
	v_pk_fma_f32 v[24:25], v[214:215], v[24:25], v[230:231]
	v_pk_fma_f32 v[26:27], v[216:217], v[26:27], v[232:233]
	v_pk_fma_f32 v[28:29], v[218:219], v[28:29], v[234:235]
	v_pk_fma_f32 v[30:31], v[220:221], v[30:31], v[236:237]
	s_nop 0
	global_store_dwordx4 v[64:65], v[16:19], off
	global_store_dwordx4 v[64:65], v[20:23], off offset:1024
	global_store_dwordx4 v[64:65], v[24:27], off offset:2048
	global_store_dwordx4 v[64:65], v[28:31], off offset:3072
	v_mov_b64_e32 v[64:65], v[58:59]
	s_add_i32 s0, s0, 1
	s_cmp_lg_u32 s0, 16
	s_cbranch_scc1 .Lln2_pair
	s_add_i32 s2, s2, s92
	s_add_i32 s10, s10, s23
	s_cmpk_gt_i32 s2, 0xff
	s_cbranch_scc0 .LBB0_1068
